# rwkv prep items: second pass of each iteration has its input loads issued one pass early into spare VGPRs (software prefetch), its load-wait ladder removed
# speedup vs baseline: 1.0003x; 1.0003x over previous
.LBB0_710:
	v_lshl_add_u64 v[140:141], s[90:91], 0, v[66:67]
	v_add_co_u32_e32 v142, vcc, 0x25801000, v140
	v_add_u32_e32 v138, 4, v58
	s_nop 0
	v_addc_co_u32_e32 v143, vcc, 0, v141, vcc
	v_cmp_lt_i32_e64 s[10:11], 0, v138
	v_add_co_u32_e32 v144, vcc, 0x25802000, v140
	s_nop 0
	v_cndmask_b32_e64 v139, 0, -1, s[10:11]
	v_cndmask_b32_e64 v138, 0, v214, s[10:11]
	v_addc_co_u32_e32 v145, vcc, 0, v141, vcc
	v_add_co_u32_e32 v140, vcc, 0x25803000, v140
	v_lshl_add_u64 v[138:139], v[66:67], 0, v[138:139]
	s_nop 0
	v_addc_co_u32_e32 v141, vcc, 0, v141, vcc
	v_lshl_add_u64 v[138:139], s[90:91], 0, v[138:139]
	v_add_co_u32_e32 v146, vcc, s33, v138
	v_lshl_add_u64 v[154:155], s[90:91], 0, v[62:63]
	s_nop 0
	v_addc_co_u32_e32 v147, vcc, 0, v139, vcc
	global_load_dwordx2 v[156:157], v[142:143], off offset:2048
	global_load_dwordx2 v[178:179], v[144:145], off offset:2048
	s_nop 0
	global_load_dwordx2 v[140:141], v[140:141], off offset:2048
	s_nop 0
	global_load_dwordx2 v[152:153], v[146:147], off offset:2048
	v_add_co_u32_e32 v142, vcc, s56, v138
	s_nop 1
	v_addc_co_u32_e32 v143, vcc, 0, v139, vcc
	v_add_co_u32_e32 v138, vcc, s57, v138
	s_nop 1
	v_addc_co_u32_e32 v139, vcc, 0, v139, vcc
	global_load_dwordx2 v[180:181], v[142:143], off offset:2048
	global_load_dwordx2 v[150:151], v[138:139], off offset:2048
	v_add_co_u32_e32 v142, vcc, 0x34c00000, v154
	v_lshl_add_u64 v[138:139], s[90:91], 0, v[64:65]
	s_nop 0
	v_addc_co_u32_e32 v143, vcc, 0, v155, vcc
	v_add_co_u32_e32 v146, vcc, 0x38c00000, v138
	s_nop 1
	v_addc_co_u32_e32 v147, vcc, 0, v139, vcc
	global_load_dwordx4 v[142:145], v[142:143], off
	s_nop 0
	global_load_dwordx2 v[182:183], v[146:147], off
	s_and_b64 vcc, exec, s[6:7]
	s_cbranch_vccnz .Lpp0_z
	v_add_co_u32_e32 v138, vcc, 0x38c02000, v138
	s_nop 1
	v_addc_co_u32_e32 v139, vcc, 0, v139, vcc
	v_add_co_u32_e32 v146, vcc, 0x19800000, v154
	s_nop 1
	v_addc_co_u32_e32 v147, vcc, 0, v155, vcc
	global_load_dwordx2 v[184:185], v[138:139], off
	s_nop 0
	global_load_dwordx4 v[146:149], v[146:147], off
	s_branch .Lpp0_j
.Lpp0_z:
	v_mov_b32_e32 v184, 0
	v_mov_b32_e32 v146, 0
	v_mov_b32_e32 v147, 0
	v_mov_b32_e32 v148, 0
	v_mov_b32_e32 v149, 0
	v_mov_b32_e32 v185, 0
.Lpp0_j:
	v_cndmask_b32_e64 v59, 0, 1.0, s[8:9]
	s_waitcnt vmcnt(13)
	v_lshlrev_b32_e32 v38, 16, v40
	s_waitcnt vmcnt(10)
	v_lshlrev_b32_e32 v39, 16, v50
	v_fma_f32 v39, v59, v39, -v38
	s_and_b64 vcc, exec, s[6:7]
	v_fmac_f32_e32 v38, v10, v39
	s_cbranch_vccnz .LBB0_712
	s_waitcnt vmcnt(9)
	v_lshlrev_b32_e32 v39, 16, v82
	v_add_f32_e32 v39, v34, v39
	v_mul_f32_e32 v39, 0xbfb8aa3b, v39
	v_exp_f32_e32 v39, v39
	s_waitcnt vmcnt(8)
	v_sub_f32_e32 v46, v46, v38
	v_add_f32_e32 v39, 1.0, v39
	v_div_scale_f32 v84, s[2:3], v39, v39, 1.0
	v_rcp_f32_e32 v85, v84
	v_div_scale_f32 v86, vcc, 1.0, v39, 1.0
	v_fma_f32 v87, -v84, v85, 1.0
	v_fmac_f32_e32 v85, v87, v85
	v_mul_f32_e32 v87, v86, v85
	v_fma_f32 v89, -v84, v87, v86
	v_fmac_f32_e32 v87, v89, v85
	v_fma_f32 v84, -v84, v87, v86
	v_div_fmas_f32 v84, v84, v85, v87
	v_div_fixup_f32 v39, v84, v39, 1.0
	v_fmac_f32_e32 v38, v46, v39
.LBB0_712:
	v_and_b32_e32 v39, 0xffff0000, v40
	v_and_b32_e32 v40, 0xffff0000, v50
	v_fma_f32 v40, v59, v40, -v39
	s_and_b64 vcc, exec, s[6:7]
	v_fmac_f32_e32 v39, v11, v40
	s_cbranch_vccnz .LBB0_714
	s_waitcnt vmcnt(9)
	v_and_b32_e32 v40, 0xffff0000, v82
	v_add_f32_e32 v40, v35, v40
	v_mul_f32_e32 v40, 0xbfb8aa3b, v40
	v_exp_f32_e32 v40, v40
	s_waitcnt vmcnt(8)
	v_sub_f32_e32 v47, v47, v39
	v_add_f32_e32 v40, 1.0, v40
	v_div_scale_f32 v46, s[2:3], v40, v40, 1.0
	v_rcp_f32_e32 v50, v46
	v_div_scale_f32 v82, vcc, 1.0, v40, 1.0
	v_fma_f32 v84, -v46, v50, 1.0
	v_fmac_f32_e32 v50, v84, v50
	v_mul_f32_e32 v84, v82, v50
	v_fma_f32 v85, -v46, v84, v82
	v_fmac_f32_e32 v84, v85, v50
	v_fma_f32 v46, -v46, v84, v82
	v_div_fmas_f32 v46, v46, v50, v84
	v_div_fixup_f32 v40, v46, v40, 1.0
	v_fmac_f32_e32 v39, v47, v40
.LBB0_714:
	v_lshlrev_b32_e32 v40, 16, v41
	s_waitcnt vmcnt(8)
	v_lshlrev_b32_e32 v46, 16, v51
	v_fma_f32 v46, v59, v46, -v40
	s_and_b64 vcc, exec, s[6:7]
	v_fmac_f32_e32 v40, v12, v46
	s_cbranch_vccnz .LBB0_716
	v_lshlrev_b32_e32 v46, 16, v83
	v_add_f32_e32 v46, v36, v46
	v_mul_f32_e32 v46, 0xbfb8aa3b, v46
	v_exp_f32_e32 v46, v46
	v_sub_f32_e32 v48, v48, v40
	v_add_f32_e32 v46, 1.0, v46
	v_div_scale_f32 v47, s[2:3], v46, v46, 1.0
	v_rcp_f32_e32 v50, v47
	v_div_scale_f32 v82, vcc, 1.0, v46, 1.0
	v_fma_f32 v84, -v47, v50, 1.0
	v_fmac_f32_e32 v50, v84, v50
	v_mul_f32_e32 v84, v82, v50
	v_fma_f32 v85, -v47, v84, v82
	v_fmac_f32_e32 v84, v85, v50
	v_fma_f32 v47, -v47, v84, v82
	v_div_fmas_f32 v47, v47, v50, v84
	v_div_fixup_f32 v46, v47, v46, 1.0
	v_fmac_f32_e32 v40, v48, v46

.LBB0_722:
	s_or_b64 exec, exec, s[10:11]
	s_cmp_eq_u32 s12, 0
	s_cbranch_scc1 .Lpp0_w8
	s_waitcnt vmcnt(7)
	s_branch .Lpp0_wd
.Lpp0_w8:
	s_waitcnt vmcnt(8)
.Lpp0_wd:
	v_lshl_add_u64 v[40:41], s[90:91], 0, v[66:67]
	v_add_co_u32_e32 v42, vcc, 0x25801000, v40
	v_add_u32_e32 v38, 4, v58
	s_nop 0
	v_addc_co_u32_e32 v43, vcc, 0, v41, vcc
	v_cmp_lt_i32_e64 s[10:11], 0, v38
	v_add_co_u32_e32 v44, vcc, 0x25802000, v40
	s_nop 0
	v_cndmask_b32_e64 v39, 0, -1, s[10:11]
	v_cndmask_b32_e64 v38, 0, v214, s[10:11]
	v_addc_co_u32_e32 v45, vcc, 0, v41, vcc
	v_add_co_u32_e32 v40, vcc, 0x25803000, v40
	v_lshl_add_u64 v[38:39], v[66:67], 0, v[38:39]
	s_nop 0
	v_addc_co_u32_e32 v41, vcc, 0, v41, vcc
	v_lshl_add_u64 v[38:39], s[90:91], 0, v[38:39]
	v_add_co_u32_e32 v46, vcc, s33, v38
	v_lshl_add_u64 v[54:55], s[90:91], 0, v[62:63]
	s_nop 0
	v_addc_co_u32_e32 v47, vcc, 0, v39, vcc
	v_mov_b32_e32 v56, v156
	v_mov_b32_e32 v57, v157
	v_mov_b32_e32 v78, v178
	v_mov_b32_e32 v79, v179
	s_nop 0
	v_mov_b32_e32 v40, v140
	v_mov_b32_e32 v41, v141
	s_nop 0
	v_mov_b32_e32 v52, v152
	v_mov_b32_e32 v53, v153
	v_add_co_u32_e32 v42, vcc, s56, v38
	s_nop 1
	v_addc_co_u32_e32 v43, vcc, 0, v39, vcc
	v_add_co_u32_e32 v38, vcc, s57, v38
	s_nop 1
	v_addc_co_u32_e32 v39, vcc, 0, v39, vcc
	v_mov_b32_e32 v80, v180
	v_mov_b32_e32 v81, v181
	v_mov_b32_e32 v50, v150
	v_mov_b32_e32 v51, v151
	v_add_co_u32_e32 v42, vcc, 0x34c00000, v54
	v_lshl_add_u64 v[38:39], s[90:91], 0, v[64:65]
	s_nop 0
	v_addc_co_u32_e32 v43, vcc, 0, v55, vcc
	v_add_co_u32_e32 v46, vcc, 0x38c00000, v38
	s_nop 1
	v_addc_co_u32_e32 v47, vcc, 0, v39, vcc
	v_mov_b32_e32 v42, v142
	v_mov_b32_e32 v43, v143
	v_mov_b32_e32 v44, v144
	v_mov_b32_e32 v45, v145
	s_nop 0
	v_mov_b32_e32 v82, v182
	v_mov_b32_e32 v83, v183
	s_and_b64 vcc, exec, s[6:7]
	s_cbranch_vccnz .LBB0_724
	v_add_co_u32_e32 v38, vcc, 0x38c02000, v38
	s_nop 1
	v_addc_co_u32_e32 v39, vcc, 0, v39, vcc
	v_add_co_u32_e32 v46, vcc, 0x19800000, v54
	s_nop 1
	v_addc_co_u32_e32 v47, vcc, 0, v55, vcc
	v_mov_b32_e32 v84, v184
	v_mov_b32_e32 v85, v185
	s_nop 0
	v_mov_b32_e32 v46, v146
	v_mov_b32_e32 v47, v147
	v_mov_b32_e32 v48, v148
	v_mov_b32_e32 v49, v149
	s_branch .LBB0_725

.LBB0_725:
	v_cndmask_b32_e64 v59, 0, 1.0, s[10:11]
	v_lshlrev_b32_e32 v38, 16, v40
	v_lshlrev_b32_e32 v39, 16, v50
	v_fma_f32 v39, v59, v39, -v38
	s_and_b64 vcc, exec, s[6:7]
	v_fmac_f32_e32 v38, v10, v39
	s_cbranch_vccnz .LBB0_727
	v_lshlrev_b32_e32 v39, 16, v84
	v_add_f32_e32 v39, v34, v39
	v_mul_f32_e32 v39, 0xbfb8aa3b, v39
	v_exp_f32_e32 v39, v39
	v_sub_f32_e32 v46, v46, v38
	v_add_f32_e32 v39, 1.0, v39
	v_div_scale_f32 v77, s[2:3], v39, v39, 1.0
	v_rcp_f32_e32 v86, v77
	v_div_scale_f32 v87, vcc, 1.0, v39, 1.0
	v_fma_f32 v89, -v77, v86, 1.0
	v_fmac_f32_e32 v86, v89, v86
	v_mul_f32_e32 v89, v87, v86
	v_fma_f32 v90, -v77, v89, v87
	v_fmac_f32_e32 v89, v90, v86
	v_fma_f32 v77, -v77, v89, v87
	v_div_fmas_f32 v77, v77, v86, v89
	v_div_fixup_f32 v39, v77, v39, 1.0
	v_fmac_f32_e32 v38, v46, v39
.LBB0_727:
	v_and_b32_e32 v39, 0xffff0000, v40
	v_and_b32_e32 v40, 0xffff0000, v50
	v_fma_f32 v40, v59, v40, -v39
	s_and_b64 vcc, exec, s[6:7]
	v_fmac_f32_e32 v39, v11, v40
	s_cbranch_vccnz .LBB0_729
	v_and_b32_e32 v40, 0xffff0000, v84
	v_add_f32_e32 v40, v35, v40
	v_mul_f32_e32 v40, 0xbfb8aa3b, v40
	v_exp_f32_e32 v40, v40
	v_sub_f32_e32 v47, v47, v39
	v_add_f32_e32 v40, 1.0, v40
	v_div_scale_f32 v46, s[2:3], v40, v40, 1.0
	v_rcp_f32_e32 v50, v46
	v_div_scale_f32 v77, vcc, 1.0, v40, 1.0
	v_fma_f32 v84, -v46, v50, 1.0
	v_fmac_f32_e32 v50, v84, v50
	v_mul_f32_e32 v84, v77, v50
	v_fma_f32 v86, -v46, v84, v77
	v_fmac_f32_e32 v84, v86, v50
	v_fma_f32 v46, -v46, v84, v77
	v_div_fmas_f32 v46, v46, v50, v84
	v_div_fixup_f32 v40, v46, v40, 1.0
	v_fmac_f32_e32 v39, v47, v40
.LBB0_729:
	v_lshlrev_b32_e32 v40, 16, v41
	v_lshlrev_b32_e32 v46, 16, v51
	v_fma_f32 v46, v59, v46, -v40
	s_and_b64 vcc, exec, s[6:7]
	v_fmac_f32_e32 v40, v12, v46
	s_cbranch_vccnz .LBB0_731
	v_lshlrev_b32_e32 v46, 16, v85
	v_add_f32_e32 v46, v36, v46
	v_mul_f32_e32 v46, 0xbfb8aa3b, v46
	v_exp_f32_e32 v46, v46
	v_sub_f32_e32 v48, v48, v40
	v_add_f32_e32 v46, 1.0, v46
	v_div_scale_f32 v47, s[2:3], v46, v46, 1.0
	v_rcp_f32_e32 v50, v47
	v_div_scale_f32 v77, vcc, 1.0, v46, 1.0
	v_fma_f32 v84, -v47, v50, 1.0
	v_fmac_f32_e32 v50, v84, v50
	v_mul_f32_e32 v84, v77, v50
	v_fma_f32 v86, -v47, v84, v77
	v_fmac_f32_e32 v84, v86, v50
	v_fma_f32 v47, -v47, v84, v77
	v_div_fmas_f32 v47, v47, v50, v84
	v_div_fixup_f32 v46, v47, v46, 1.0
	v_fmac_f32_e32 v40, v48, v46

.LBB0_2331:
	v_lshl_add_u64 v[140:141], s[90:91], 0, v[66:67]
	v_add_co_u32_e32 v142, vcc, 0x25801000, v140
	v_add_u32_e32 v138, 4, v58
	s_nop 0
	v_addc_co_u32_e32 v143, vcc, 0, v141, vcc
	v_cmp_lt_i32_e64 s[10:11], 0, v138
	v_add_co_u32_e32 v144, vcc, 0x25802000, v140
	s_nop 0
	v_cndmask_b32_e64 v139, 0, -1, s[10:11]
	v_cndmask_b32_e64 v138, 0, v215, s[10:11]
	v_addc_co_u32_e32 v145, vcc, 0, v141, vcc
	v_add_co_u32_e32 v140, vcc, 0x25803000, v140
	v_lshl_add_u64 v[138:139], v[66:67], 0, v[138:139]
	s_nop 0
	v_addc_co_u32_e32 v141, vcc, 0, v141, vcc
	v_lshl_add_u64 v[138:139], s[90:91], 0, v[138:139]
	v_add_co_u32_e32 v146, vcc, s33, v138
	v_lshl_add_u64 v[154:155], s[90:91], 0, v[62:63]
	s_nop 0
	v_addc_co_u32_e32 v147, vcc, 0, v139, vcc
	global_load_dwordx2 v[156:157], v[142:143], off offset:2048
	global_load_dwordx2 v[178:179], v[144:145], off offset:2048
	s_nop 0
	global_load_dwordx2 v[140:141], v[140:141], off offset:2048
	s_nop 0
	global_load_dwordx2 v[152:153], v[146:147], off offset:2048
	v_add_co_u32_e32 v142, vcc, s56, v138
	s_nop 1
	v_addc_co_u32_e32 v143, vcc, 0, v139, vcc
	v_add_co_u32_e32 v138, vcc, s57, v138
	s_nop 1
	v_addc_co_u32_e32 v139, vcc, 0, v139, vcc
	global_load_dwordx2 v[180:181], v[142:143], off offset:2048
	global_load_dwordx2 v[150:151], v[138:139], off offset:2048
	v_add_co_u32_e32 v142, vcc, 0x34c00000, v154
	v_lshl_add_u64 v[138:139], s[90:91], 0, v[64:65]
	s_nop 0
	v_addc_co_u32_e32 v143, vcc, 0, v155, vcc
	v_add_co_u32_e32 v146, vcc, 0x38c00000, v138
	s_nop 1
	v_addc_co_u32_e32 v147, vcc, 0, v139, vcc
	global_load_dwordx4 v[142:145], v[142:143], off
	s_nop 0
	global_load_dwordx2 v[182:183], v[146:147], off
	s_and_b64 vcc, exec, s[6:7]
	s_cbranch_vccnz .Lpp1_z
	v_add_co_u32_e32 v138, vcc, 0x38c02000, v138
	s_nop 1
	v_addc_co_u32_e32 v139, vcc, 0, v139, vcc
	v_add_co_u32_e32 v146, vcc, 0x19800000, v154
	s_nop 1
	v_addc_co_u32_e32 v147, vcc, 0, v155, vcc
	global_load_dwordx2 v[184:185], v[138:139], off
	s_nop 0
	global_load_dwordx4 v[146:149], v[146:147], off
	s_branch .Lpp1_j

.Lpp1_wd:
	v_lshl_add_u64 v[40:41], s[90:91], 0, v[66:67]
	v_add_co_u32_e32 v42, vcc, 0x25801000, v40
	v_add_u32_e32 v38, 4, v58
	s_nop 0
	v_addc_co_u32_e32 v43, vcc, 0, v41, vcc
	v_cmp_lt_i32_e64 s[10:11], 0, v38
	v_add_co_u32_e32 v44, vcc, 0x25802000, v40
	s_nop 0
	v_cndmask_b32_e64 v39, 0, -1, s[10:11]
	v_cndmask_b32_e64 v38, 0, v215, s[10:11]
	v_addc_co_u32_e32 v45, vcc, 0, v41, vcc
	v_add_co_u32_e32 v40, vcc, 0x25803000, v40
	v_lshl_add_u64 v[38:39], v[66:67], 0, v[38:39]
	s_nop 0
	v_addc_co_u32_e32 v41, vcc, 0, v41, vcc
	v_lshl_add_u64 v[38:39], s[90:91], 0, v[38:39]
	v_add_co_u32_e32 v46, vcc, s33, v38
	v_lshl_add_u64 v[54:55], s[90:91], 0, v[62:63]
	s_nop 0
	v_addc_co_u32_e32 v47, vcc, 0, v39, vcc
	v_mov_b32_e32 v56, v156
	v_mov_b32_e32 v57, v157
	v_mov_b32_e32 v78, v178
	v_mov_b32_e32 v79, v179
	s_nop 0
	v_mov_b32_e32 v40, v140
	v_mov_b32_e32 v41, v141
	s_nop 0
	v_mov_b32_e32 v52, v152
	v_mov_b32_e32 v53, v153
	v_add_co_u32_e32 v42, vcc, s56, v38
	s_nop 1
	v_addc_co_u32_e32 v43, vcc, 0, v39, vcc
	v_add_co_u32_e32 v38, vcc, s57, v38
	s_nop 1
	v_addc_co_u32_e32 v39, vcc, 0, v39, vcc
	v_mov_b32_e32 v80, v180
	v_mov_b32_e32 v81, v181
	v_mov_b32_e32 v50, v150
	v_mov_b32_e32 v51, v151
	v_add_co_u32_e32 v42, vcc, 0x34c00000, v54
	v_lshl_add_u64 v[38:39], s[90:91], 0, v[64:65]
	s_nop 0
	v_addc_co_u32_e32 v43, vcc, 0, v55, vcc
	v_add_co_u32_e32 v46, vcc, 0x38c00000, v38
	s_nop 1
	v_addc_co_u32_e32 v47, vcc, 0, v39, vcc
	v_mov_b32_e32 v42, v142
	v_mov_b32_e32 v43, v143
	v_mov_b32_e32 v44, v144
	v_mov_b32_e32 v45, v145
	s_nop 0
	v_mov_b32_e32 v82, v182
	v_mov_b32_e32 v83, v183
	s_and_b64 vcc, exec, s[6:7]
	s_cbranch_vccnz .LBB0_2345
	v_add_co_u32_e32 v38, vcc, 0x38c02000, v38
	s_nop 1
	v_addc_co_u32_e32 v39, vcc, 0, v39, vcc
	v_add_co_u32_e32 v46, vcc, 0x19800000, v54
	s_nop 1
	v_addc_co_u32_e32 v47, vcc, 0, v55, vcc
	v_mov_b32_e32 v84, v184
	v_mov_b32_e32 v85, v185
	s_nop 0
	v_mov_b32_e32 v46, v146
	v_mov_b32_e32 v47, v147
	v_mov_b32_e32 v48, v148
	v_mov_b32_e32 v49, v149
	s_branch .LBB0_2346
